# GEMM tile preheaders: 128 accumulator registers cleared with 64 v_mov_b64 instead of 128 v_mov_b32
# baseline (speedup 1.0000x reference)
.LBB0_177:
	s_ashr_i32 s15, s14, 31
	s_lshl_b64 s[16:17], s[14:15], 19
	v_readlane_b32 s18, v247, 5
	v_readlane_b32 s19, v247, 6
	s_add_u32 s16, s18, s16
	s_addc_u32 s17, s19, s17
	s_and_b64 s[18:19], s[6:7], exec
	s_cselect_b32 s9, s17, s23
	s_cselect_b32 s15, s16, s22
	s_ashr_i32 s13, s12, 31
	s_lshl_b64 s[18:19], s[12:13], 19
	s_add_u32 s18, s44, s18
	s_addc_u32 s19, s43, s19
	s_and_b64 s[30:31], s[6:7], exec
	s_cselect_b32 s13, s19, s27
	s_cselect_b32 s56, s18, s26
	s_add_u32 s22, s22, 0x40080
	s_addc_u32 s23, s23, 0
	s_add_u32 s57, s26, 0x100
	v_mov_b64_e32 v[0:1], 0
	v_mov_b64_e32 v[2:3], 0
	v_mov_b64_e32 v[4:5], 0
	v_mov_b64_e32 v[6:7], 0
	v_mov_b64_e32 v[8:9], 0
	v_mov_b64_e32 v[10:11], 0
	v_mov_b64_e32 v[12:13], 0
	v_mov_b64_e32 v[14:15], 0
	v_mov_b64_e32 v[16:17], 0
	v_mov_b64_e32 v[18:19], 0
	v_mov_b64_e32 v[20:21], 0
	v_mov_b64_e32 v[22:23], 0
	v_mov_b64_e32 v[24:25], 0
	v_mov_b64_e32 v[26:27], 0
	v_mov_b64_e32 v[28:29], 0
	v_mov_b64_e32 v[30:31], 0
	v_mov_b64_e32 v[32:33], 0
	v_mov_b64_e32 v[34:35], 0
	v_mov_b64_e32 v[36:37], 0
	v_mov_b64_e32 v[38:39], 0
	v_mov_b64_e32 v[40:41], 0
	v_mov_b64_e32 v[42:43], 0
	v_mov_b64_e32 v[44:45], 0
	v_mov_b64_e32 v[46:47], 0
	v_mov_b64_e32 v[48:49], 0
	v_mov_b64_e32 v[50:51], 0
	v_mov_b64_e32 v[52:53], 0
	v_mov_b64_e32 v[54:55], 0
	v_mov_b64_e32 v[56:57], 0
	v_mov_b64_e32 v[58:59], 0
	v_mov_b64_e32 v[60:61], 0
	v_mov_b64_e32 v[62:63], 0
	v_mov_b64_e32 v[64:65], 0
	v_mov_b64_e32 v[66:67], 0
	v_mov_b64_e32 v[68:69], 0
	v_mov_b64_e32 v[70:71], 0
	v_mov_b64_e32 v[72:73], 0
	v_mov_b64_e32 v[74:75], 0
	v_mov_b64_e32 v[76:77], 0
	v_mov_b64_e32 v[78:79], 0
	v_mov_b64_e32 v[80:81], 0
	v_mov_b64_e32 v[82:83], 0
	v_mov_b64_e32 v[84:85], 0
	v_mov_b64_e32 v[86:87], 0
	v_mov_b64_e32 v[88:89], 0
	v_mov_b64_e32 v[90:91], 0
	v_mov_b64_e32 v[92:93], 0
	v_mov_b64_e32 v[94:95], 0
	v_mov_b64_e32 v[96:97], 0
	v_mov_b64_e32 v[98:99], 0
	v_mov_b64_e32 v[100:101], 0
	v_mov_b64_e32 v[102:103], 0
	v_mov_b64_e32 v[104:105], 0
	v_mov_b64_e32 v[106:107], 0
	v_mov_b64_e32 v[108:109], 0
	v_mov_b64_e32 v[110:111], 0
	v_mov_b64_e32 v[112:113], 0
	v_mov_b64_e32 v[114:115], 0
	v_mov_b64_e32 v[116:117], 0
	v_mov_b64_e32 v[118:119], 0
	v_mov_b64_e32 v[120:121], 0
	v_mov_b64_e32 v[122:123], 0
	v_mov_b64_e32 v[124:125], 0
	v_mov_b64_e32 v[126:127], 0
	s_addc_u32 s58, s27, 0
	s_mov_b32 s59, -2

.LBB0_775:
	s_ashr_i32 s15, s14, 31
	s_lshl_b64 s[16:17], s[14:15], 19
	v_readlane_b32 s18, v250, 10
	v_readlane_b32 s19, v250, 11
	s_add_u32 s16, s18, s16
	s_addc_u32 s17, s19, s17
	s_and_b64 s[18:19], s[8:9], exec
	s_cselect_b32 s15, s17, s23
	s_cselect_b32 s51, s16, s22
	s_ashr_i32 s13, s12, 31
	s_lshl_b64 s[18:19], s[12:13], 19
	s_add_u32 s18, s5, s18
	s_addc_u32 s19, s34, s19
	s_and_b64 s[30:31], s[8:9], exec
	s_cselect_b32 s13, s19, s27
	s_cselect_b32 s52, s18, s26
	s_add_u32 s22, s22, 0x40080
	s_addc_u32 s23, s23, 0
	s_add_u32 s53, s26, 0x100
	v_mov_b64_e32 v[0:1], 0
	v_mov_b64_e32 v[2:3], 0
	v_mov_b64_e32 v[4:5], 0
	v_mov_b64_e32 v[6:7], 0
	v_mov_b64_e32 v[8:9], 0
	v_mov_b64_e32 v[10:11], 0
	v_mov_b64_e32 v[12:13], 0
	v_mov_b64_e32 v[14:15], 0
	v_mov_b64_e32 v[16:17], 0
	v_mov_b64_e32 v[18:19], 0
	v_mov_b64_e32 v[20:21], 0
	v_mov_b64_e32 v[22:23], 0
	v_mov_b64_e32 v[24:25], 0
	v_mov_b64_e32 v[26:27], 0
	v_mov_b64_e32 v[28:29], 0
	v_mov_b64_e32 v[30:31], 0
	v_mov_b64_e32 v[32:33], 0
	v_mov_b64_e32 v[34:35], 0
	v_mov_b64_e32 v[36:37], 0
	v_mov_b64_e32 v[38:39], 0
	v_mov_b64_e32 v[40:41], 0
	v_mov_b64_e32 v[42:43], 0
	v_mov_b64_e32 v[44:45], 0
	v_mov_b64_e32 v[46:47], 0
	v_mov_b64_e32 v[48:49], 0
	v_mov_b64_e32 v[50:51], 0
	v_mov_b64_e32 v[52:53], 0
	v_mov_b64_e32 v[54:55], 0
	v_mov_b64_e32 v[56:57], 0
	v_mov_b64_e32 v[58:59], 0
	v_mov_b64_e32 v[60:61], 0
	v_mov_b64_e32 v[62:63], 0
	v_mov_b64_e32 v[64:65], 0
	v_mov_b64_e32 v[66:67], 0
	v_mov_b64_e32 v[68:69], 0
	v_mov_b64_e32 v[70:71], 0
	v_mov_b64_e32 v[72:73], 0
	v_mov_b64_e32 v[74:75], 0
	v_mov_b64_e32 v[76:77], 0
	v_mov_b64_e32 v[78:79], 0
	v_mov_b64_e32 v[80:81], 0
	v_mov_b64_e32 v[82:83], 0
	v_mov_b64_e32 v[84:85], 0
	v_mov_b64_e32 v[86:87], 0
	v_mov_b64_e32 v[88:89], 0
	v_mov_b64_e32 v[90:91], 0
	v_mov_b64_e32 v[92:93], 0
	v_mov_b64_e32 v[94:95], 0
	v_mov_b64_e32 v[96:97], 0
	v_mov_b64_e32 v[98:99], 0
	v_mov_b64_e32 v[100:101], 0
	v_mov_b64_e32 v[102:103], 0
	v_mov_b64_e32 v[104:105], 0
	v_mov_b64_e32 v[106:107], 0
	v_mov_b64_e32 v[108:109], 0
	v_mov_b64_e32 v[110:111], 0
	v_mov_b64_e32 v[112:113], 0
	v_mov_b64_e32 v[114:115], 0
	v_mov_b64_e32 v[116:117], 0
	v_mov_b64_e32 v[118:119], 0
	v_mov_b64_e32 v[120:121], 0
	v_mov_b64_e32 v[122:123], 0
	v_mov_b64_e32 v[124:125], 0
	v_mov_b64_e32 v[126:127], 0
	s_addc_u32 s54, s27, 0
	s_mov_b32 s55, -2
	s_waitcnt lgkmcnt(0)

.LBB0_889:
	s_ashr_i32 s13, s12, 31
	s_lshl_b64 s[14:15], s[12:13], 19
	v_readlane_b32 s16, v247, 5
	v_readlane_b32 s17, v247, 6
	s_add_u32 s14, s16, s14
	s_addc_u32 s15, s17, s15
	s_and_b64 s[16:17], s[6:7], exec
	s_cselect_b32 s13, s15, s1
	s_cselect_b32 s46, s14, s0
	s_ashr_i32 s11, s10, 31
	s_lshl_b64 s[16:17], s[10:11], 19
	s_add_u32 s16, s5, s16
	s_addc_u32 s17, s26, s17
	s_and_b64 s[22:23], s[6:7], exec
	s_cselect_b32 s11, s17, s19
	s_cselect_b32 s47, s16, s18
	s_add_u32 s0, s0, 0x40080
	s_addc_u32 s1, s1, 0
	s_add_u32 s48, s18, 0x100
	v_mov_b64_e32 v[0:1], 0
	v_mov_b64_e32 v[2:3], 0
	v_mov_b64_e32 v[4:5], 0
	v_mov_b64_e32 v[6:7], 0
	v_mov_b64_e32 v[8:9], 0
	v_mov_b64_e32 v[10:11], 0
	v_mov_b64_e32 v[12:13], 0
	v_mov_b64_e32 v[14:15], 0
	v_mov_b64_e32 v[16:17], 0
	v_mov_b64_e32 v[18:19], 0
	v_mov_b64_e32 v[20:21], 0
	v_mov_b64_e32 v[22:23], 0
	v_mov_b64_e32 v[24:25], 0
	v_mov_b64_e32 v[26:27], 0
	v_mov_b64_e32 v[28:29], 0
	v_mov_b64_e32 v[30:31], 0
	v_mov_b64_e32 v[32:33], 0
	v_mov_b64_e32 v[34:35], 0
	v_mov_b64_e32 v[36:37], 0
	v_mov_b64_e32 v[38:39], 0
	v_mov_b64_e32 v[40:41], 0
	v_mov_b64_e32 v[42:43], 0
	v_mov_b64_e32 v[44:45], 0
	v_mov_b64_e32 v[46:47], 0
	v_mov_b64_e32 v[48:49], 0
	v_mov_b64_e32 v[50:51], 0
	v_mov_b64_e32 v[52:53], 0
	v_mov_b64_e32 v[54:55], 0
	v_mov_b64_e32 v[56:57], 0
	v_mov_b64_e32 v[58:59], 0
	v_mov_b64_e32 v[60:61], 0
	v_mov_b64_e32 v[62:63], 0
	v_mov_b64_e32 v[64:65], 0
	v_mov_b64_e32 v[66:67], 0
	v_mov_b64_e32 v[68:69], 0
	v_mov_b64_e32 v[70:71], 0
	v_mov_b64_e32 v[72:73], 0
	v_mov_b64_e32 v[74:75], 0
	v_mov_b64_e32 v[76:77], 0
	v_mov_b64_e32 v[78:79], 0
	v_mov_b64_e32 v[80:81], 0
	v_mov_b64_e32 v[82:83], 0
	v_mov_b64_e32 v[84:85], 0
	v_mov_b64_e32 v[86:87], 0
	v_mov_b64_e32 v[88:89], 0
	v_mov_b64_e32 v[90:91], 0
	v_mov_b64_e32 v[92:93], 0
	v_mov_b64_e32 v[94:95], 0
	v_mov_b64_e32 v[96:97], 0
	v_mov_b64_e32 v[98:99], 0
	v_mov_b64_e32 v[100:101], 0
	v_mov_b64_e32 v[102:103], 0
	v_mov_b64_e32 v[104:105], 0
	v_mov_b64_e32 v[106:107], 0
	v_mov_b64_e32 v[108:109], 0
	v_mov_b64_e32 v[110:111], 0
	v_mov_b64_e32 v[112:113], 0
	v_mov_b64_e32 v[114:115], 0
	v_mov_b64_e32 v[116:117], 0
	v_mov_b64_e32 v[118:119], 0
	v_mov_b64_e32 v[120:121], 0
	v_mov_b64_e32 v[122:123], 0
	v_mov_b64_e32 v[124:125], 0
	v_mov_b64_e32 v[126:127], 0
	s_addc_u32 s49, s19, 0
	s_mov_b32 s50, -2

.LBB0_985:
	s_ashr_i32 s23, s22, 31
	s_lshl_b64 s[26:27], s[22:23], 21
	v_readlane_b32 s30, v250, 6
	v_readlane_b32 s31, v250, 7
	s_add_u32 s26, s30, s26
	s_addc_u32 s27, s31, s27
	s_and_b64 s[30:31], s[6:7], exec
	s_cselect_b32 s23, s27, s9
	s_cselect_b32 s53, s26, s8
	s_ashr_i32 s19, s18, 31
	s_lshl_b64 s[30:31], s[18:19], 21
	s_add_u32 s30, s5, s30
	s_addc_u32 s31, s42, s31
	s_and_b64 s[36:37], s[6:7], exec
	s_cselect_b32 s19, s31, s35
	s_cselect_b32 s54, s30, s34
	s_add_u32 s8, s8, 0x100080
	s_addc_u32 s9, s9, 0
	s_add_u32 s55, s34, 0x100
	v_mov_b64_e32 v[0:1], 0
	v_mov_b64_e32 v[2:3], 0
	v_mov_b64_e32 v[4:5], 0
	v_mov_b64_e32 v[6:7], 0
	v_mov_b64_e32 v[8:9], 0
	v_mov_b64_e32 v[10:11], 0
	v_mov_b64_e32 v[12:13], 0
	v_mov_b64_e32 v[14:15], 0
	v_mov_b64_e32 v[16:17], 0
	v_mov_b64_e32 v[18:19], 0
	v_mov_b64_e32 v[20:21], 0
	v_mov_b64_e32 v[22:23], 0
	v_mov_b64_e32 v[24:25], 0
	v_mov_b64_e32 v[26:27], 0
	v_mov_b64_e32 v[28:29], 0
	v_mov_b64_e32 v[30:31], 0
	v_mov_b64_e32 v[32:33], 0
	v_mov_b64_e32 v[34:35], 0
	v_mov_b64_e32 v[36:37], 0
	v_mov_b64_e32 v[38:39], 0
	v_mov_b64_e32 v[40:41], 0
	v_mov_b64_e32 v[42:43], 0
	v_mov_b64_e32 v[44:45], 0
	v_mov_b64_e32 v[46:47], 0
	v_mov_b64_e32 v[48:49], 0
	v_mov_b64_e32 v[50:51], 0
	v_mov_b64_e32 v[52:53], 0
	v_mov_b64_e32 v[54:55], 0
	v_mov_b64_e32 v[56:57], 0
	v_mov_b64_e32 v[58:59], 0
	v_mov_b64_e32 v[60:61], 0
	v_mov_b64_e32 v[62:63], 0
	v_mov_b64_e32 v[64:65], 0
	v_mov_b64_e32 v[66:67], 0
	v_mov_b64_e32 v[68:69], 0
	v_mov_b64_e32 v[70:71], 0
	v_mov_b64_e32 v[72:73], 0
	v_mov_b64_e32 v[74:75], 0
	v_mov_b64_e32 v[76:77], 0
	v_mov_b64_e32 v[78:79], 0
	v_mov_b64_e32 v[80:81], 0
	v_mov_b64_e32 v[82:83], 0
	v_mov_b64_e32 v[84:85], 0
	v_mov_b64_e32 v[86:87], 0
	v_mov_b64_e32 v[88:89], 0
	v_mov_b64_e32 v[90:91], 0
	v_mov_b64_e32 v[92:93], 0
	v_mov_b64_e32 v[94:95], 0
	v_mov_b64_e32 v[96:97], 0
	v_mov_b64_e32 v[98:99], 0
	v_mov_b64_e32 v[100:101], 0
	v_mov_b64_e32 v[102:103], 0
	v_mov_b64_e32 v[104:105], 0
	v_mov_b64_e32 v[106:107], 0
	v_mov_b64_e32 v[108:109], 0
	v_mov_b64_e32 v[110:111], 0
	v_mov_b64_e32 v[112:113], 0
	v_mov_b64_e32 v[114:115], 0
	v_mov_b64_e32 v[116:117], 0
	v_mov_b64_e32 v[118:119], 0
	v_mov_b64_e32 v[120:121], 0
	v_mov_b64_e32 v[122:123], 0
	v_mov_b64_e32 v[124:125], 0
	v_mov_b64_e32 v[126:127], 0
	s_addc_u32 s56, s35, 0
	s_mov_b32 s57, -2
	s_waitcnt lgkmcnt(0)
